# grid barrier: non-leader WGs poll the global TOPGEN word directly (skip per-XCD XGEN hop); ws pointer from spill lanes instead of s_load
# speedup vs baseline: 1.0064x; 1.0064x over previous
.LBB0_66:
	s_mov_b64 s[4:5], s[0:1]
	v_readlane_b32 s33, v255, 2
	s_waitcnt vmcnt(0)
	v_mov_b32_e32 v0, v252
	s_barrier
	s_nop 0
	v_cmp_eq_u32_e32 vcc, 0, v0
	s_and_saveexec_b64 s[2:3], vcc
	s_cbranch_execz .LBB0_118
	s_add_i32 s6, 0, 0x22400
	v_mov_b32_e32 v0, s6
	v_readlane_b32 s4, v255, 0
	v_readlane_b32 s5, v255, 1
	s_waitcnt vmcnt(0) expcnt(0) lgkmcnt(0)
	ds_read_b32 v2, v0
	s_add_i32 s6, 0, 0x22404
	v_mov_b32_e32 v0, s6
	ds_read_b32 v0, v0
	s_waitcnt lgkmcnt(1)
	v_cmp_ne_u32_e32 vcc, 0, v2
	s_cbranch_vccnz .LBB0_82
	s_add_u32 s6, s4, 0xf4b0200
	s_addc_u32 s7, s5, 0
	s_add_u32 s8, s4, 0xf4b0400
	s_addc_u32 s9, s5, 0
	s_add_u32 s10, s4, 0xf4b0500
	s_addc_u32 s11, s5, 0
	s_add_u32 s12, s4, 0xf4b0600
	s_addc_u32 s13, s5, 0
	s_add_u32 s14, s4, 0xf4b0700
	s_addc_u32 s15, s5, 0
	s_add_u32 s16, s4, 0xf4b0800
	s_addc_u32 s17, s5, 0
	s_add_u32 s24, s4, 0xf4b0900
	s_addc_u32 s25, s5, 0
	s_add_u32 s26, s4, 0xf4b0a00
	s_addc_u32 s27, s5, 0
	s_add_u32 s28, s4, 0xf4b0b00
	s_addc_u32 s29, s5, 0
	s_add_u32 s30, s4, 0xf4b0c00
	s_addc_u32 s31, s5, 0
	s_add_u32 s34, s4, 0xf4b0d00
	s_addc_u32 s35, s5, 0
	s_add_u32 s36, s4, 0xf4b0e00
	s_addc_u32 s37, s5, 0
	s_add_u32 s38, s4, 0xf4b0f00
	s_addc_u32 s39, s5, 0
	s_add_u32 s40, s4, 0xf4b1000
	s_addc_u32 s41, s5, 0
	s_add_u32 s42, s4, 0xf4b1100
	s_addc_u32 s43, s5, 0
	s_add_u32 s44, s4, 0xf4b1200
	s_addc_u32 s45, s5, 0
	s_mul_i32 s52, s21, s19
	s_add_u32 s46, s4, 0xf4b1300
	s_mul_i32 s52, s52, s20
	s_addc_u32 s47, s5, 0
	s_mov_b32 s53, 1
	v_mov_b32_e32 v16, 0
	s_branch .LBB0_70

.LBB0_84:
	s_or_b64 exec, exec, s[8:9]
	v_cvt_f32_u32_e32 v4, v2
	s_waitcnt vmcnt(0)
	v_readfirstlane_b32 s6, v3
	v_sub_u32_e32 v3, 0, v2
	v_rcp_iflag_f32_e32 v4, v4
	v_add_u32_e32 v5, s6, v1
	v_mul_f32_e32 v4, 0x4f7ffffe, v4
	v_cvt_u32_f32_e32 v4, v4
	v_mul_lo_u32 v1, v3, v4
	v_mul_hi_u32 v1, v4, v1
	v_add_u32_e32 v1, v4, v1
	v_mul_hi_u32 v1, v5, v1
	v_mul_lo_u32 v3, v1, v2
	v_sub_u32_e32 v3, v5, v3
	v_add_u32_e32 v4, 1, v1
	v_cmp_ge_u32_e32 vcc, v3, v2
	s_nop 1
	v_cndmask_b32_e32 v1, v1, v4, vcc
	v_sub_u32_e32 v4, v3, v2
	v_cndmask_b32_e32 v3, v3, v4, vcc
	v_add_u32_e32 v4, 1, v1
	v_cmp_ge_u32_e32 vcc, v3, v2
	v_add_u32_e32 v3, 1, v5
	s_nop 0
	v_cndmask_b32_e32 v1, v1, v4, vcc
	v_mul_lo_u32 v4, v2, v1
	v_add_u32_e32 v2, v4, v2
	v_cmp_ne_u32_e32 vcc, v3, v2
	s_and_saveexec_b64 s[6:7], vcc
	s_xor_b64 s[6:7], exec, s[6:7]
	s_cbranch_execz .LBB0_98
	s_add_i32 s8, s30, 0x900
	s_mov_b32 s9, 0
	s_lshl_b64 s[8:9], s[8:9], 2
	s_add_u32 s12, s4, 0xf4b3500
	s_addc_u32 s13, s5, 0
	s_waitcnt lgkmcnt(0)
	v_mov_b32_e32 v0, 0
	global_load_dword v2, v0, s[12:13] sc1
	s_waitcnt vmcnt(0)
	v_cmp_eq_u32_e32 vcc, v2, v1
	s_and_saveexec_b64 s[8:9], vcc
	s_cbranch_execz .LBB0_97
	s_add_u32 s10, s4, 0xf4b0200
	s_addc_u32 s11, s5, 0
	s_mov_b32 s31, 1
	s_mov_b64 s[14:15], 0
	s_branch .LBB0_88

.LBB0_397:
	s_mov_b64 s[4:5], s[0:1]
	v_readlane_b32 s34, v255, 2
	s_waitcnt vmcnt(0)
	v_mov_b32_e32 v0, v252
	s_waitcnt vmcnt(0) lgkmcnt(0)
	s_barrier
	s_nop 0
	v_cmp_eq_u32_e32 vcc, 0, v0
	s_and_saveexec_b64 s[2:3], vcc
	s_cbranch_execz .LBB0_449
	v_readlane_b32 s6, v255, 9
	v_readlane_b32 s4, v255, 0
	v_readlane_b32 s5, v255, 1
	s_waitcnt vmcnt(0) expcnt(0) lgkmcnt(0)
	v_mov_b32_e32 v0, s6
	ds_read_b32 v3, v0
	v_readlane_b32 s6, v255, 10
	s_waitcnt lgkmcnt(0)
	v_cmp_ne_u32_e32 vcc, 0, v3
	v_mov_b32_e32 v0, s6
	ds_read_b32 v2, v0
	s_cbranch_vccnz .LBB0_413
	s_add_u32 s6, s4, 0xf4b0200
	s_addc_u32 s7, s5, 0
	s_add_u32 s8, s4, 0xf4b0400
	s_addc_u32 s9, s5, 0
	s_add_u32 s10, s4, 0xf4b0500
	s_addc_u32 s11, s5, 0
	s_add_u32 s12, s4, 0xf4b0600
	s_addc_u32 s13, s5, 0
	s_add_u32 s14, s4, 0xf4b0700
	s_addc_u32 s15, s5, 0
	s_add_u32 s16, s4, 0xf4b0800
	s_addc_u32 s17, s5, 0
	s_add_u32 s86, s4, 0xf4b0900
	s_addc_u32 s87, s5, 0
	s_add_u32 s88, s4, 0xf4b0a00
	s_addc_u32 s89, s5, 0
	s_add_u32 s90, s4, 0xf4b0b00
	s_addc_u32 s91, s5, 0
	s_mov_b64 s[78:79], s[92:93]
	s_add_u32 s92, s4, 0xf4b0c00
	s_addc_u32 s93, s5, 0
	s_add_u32 s94, s4, 0xf4b0d00
	s_addc_u32 s95, s5, 0
	s_add_u32 s96, s4, 0xf4b0e00
	s_addc_u32 s97, s5, 0
	s_add_u32 s38, s4, 0xf4b0f00
	s_addc_u32 s39, s5, 0
	s_add_u32 s36, s4, 0xf4b1000
	s_addc_u32 s37, s5, 0
	s_add_u32 s42, s4, 0xf4b1100
	s_addc_u32 s43, s5, 0
	s_add_u32 s72, s4, 0xf4b1200
	s_addc_u32 s73, s5, 0
	s_add_u32 s74, s4, 0xf4b1300
	s_addc_u32 s75, s5, 0
	s_mov_b32 s44, 1
	s_branch .LBB0_401

.LBB0_415:
	s_or_b64 exec, exec, s[8:9]
	v_cvt_f32_u32_e32 v5, v3
	s_waitcnt vmcnt(0)
	v_readfirstlane_b32 s6, v4
	v_sub_u32_e32 v4, 0, v3
	v_rcp_iflag_f32_e32 v5, v5
	v_add_u32_e32 v6, s6, v0
	v_mul_f32_e32 v5, 0x4f7ffffe, v5
	v_cvt_u32_f32_e32 v5, v5
	v_mul_lo_u32 v0, v4, v5
	v_mul_hi_u32 v0, v5, v0
	v_add_u32_e32 v0, v5, v0
	v_mul_hi_u32 v0, v6, v0
	v_mul_lo_u32 v4, v0, v3
	v_sub_u32_e32 v4, v6, v4
	v_add_u32_e32 v5, 1, v0
	v_cmp_ge_u32_e32 vcc, v4, v3
	s_nop 1
	v_cndmask_b32_e32 v0, v0, v5, vcc
	v_sub_u32_e32 v5, v4, v3
	v_cndmask_b32_e32 v4, v4, v5, vcc
	v_add_u32_e32 v5, 1, v0
	v_cmp_ge_u32_e32 vcc, v4, v3
	v_add_u32_e32 v4, 1, v6
	s_nop 0
	v_cndmask_b32_e32 v0, v0, v5, vcc
	v_mul_lo_u32 v5, v3, v0
	v_add_u32_e32 v3, v5, v3
	v_cmp_ne_u32_e32 vcc, v4, v3
	s_and_saveexec_b64 s[6:7], vcc
	s_xor_b64 s[6:7], exec, s[6:7]
	s_cbranch_execz .LBB0_429
	s_add_i32 s34, s42, 0x900
	s_lshl_b64 s[8:9], s[34:35], 2
	s_add_u32 s12, s4, 0xf4b3500
	s_addc_u32 s13, s5, 0
	s_waitcnt lgkmcnt(0)
	global_load_dword v2, v1, s[12:13] sc1
	s_waitcnt vmcnt(0)
	v_cmp_eq_u32_e32 vcc, v2, v0
	s_and_saveexec_b64 s[8:9], vcc
	s_cbranch_execz .LBB0_428
	s_add_u32 s10, s4, 0xf4b0200
	s_addc_u32 s11, s5, 0
	s_mov_b32 s34, 1
	s_mov_b64 s[14:15], 0
	s_branch .LBB0_419

.LBB0_471:
	s_mov_b64 s[4:5], s[0:1]
	v_readlane_b32 s34, v255, 2
	s_waitcnt vmcnt(0)
	v_mov_b32_e32 v0, v252
	s_barrier
	s_nop 0
	v_cmp_eq_u32_e32 vcc, 0, v0
	s_and_saveexec_b64 s[2:3], vcc
	s_cbranch_execz .LBB0_523
	v_readlane_b32 s6, v255, 9
	v_readlane_b32 s4, v255, 0
	v_readlane_b32 s5, v255, 1
	s_waitcnt vmcnt(0) expcnt(0) lgkmcnt(0)
	v_mov_b32_e32 v0, s6
	ds_read_b32 v3, v0
	v_readlane_b32 s6, v255, 10
	s_waitcnt lgkmcnt(0)
	v_cmp_ne_u32_e32 vcc, 0, v3
	v_mov_b32_e32 v0, s6
	ds_read_b32 v2, v0
	s_cbranch_vccnz .LBB0_487
	s_add_u32 s6, s4, 0xf4b0200
	s_addc_u32 s7, s5, 0
	s_add_u32 s8, s4, 0xf4b0400
	s_addc_u32 s9, s5, 0
	s_add_u32 s10, s4, 0xf4b0500
	s_addc_u32 s11, s5, 0
	s_add_u32 s12, s4, 0xf4b0600
	s_addc_u32 s13, s5, 0
	s_add_u32 s14, s4, 0xf4b0700
	s_addc_u32 s15, s5, 0
	s_add_u32 s16, s4, 0xf4b0800
	s_addc_u32 s17, s5, 0
	s_add_u32 s86, s4, 0xf4b0900
	s_addc_u32 s87, s5, 0
	s_add_u32 s88, s4, 0xf4b0a00
	s_addc_u32 s89, s5, 0
	s_add_u32 s90, s4, 0xf4b0b00
	s_addc_u32 s91, s5, 0
	s_mov_b64 s[78:79], s[92:93]
	s_add_u32 s92, s4, 0xf4b0c00
	s_addc_u32 s93, s5, 0
	s_add_u32 s94, s4, 0xf4b0d00
	s_addc_u32 s95, s5, 0
	s_add_u32 s96, s4, 0xf4b0e00
	s_addc_u32 s97, s5, 0
	s_add_u32 s38, s4, 0xf4b0f00
	s_addc_u32 s39, s5, 0
	s_add_u32 s36, s4, 0xf4b1000
	s_addc_u32 s37, s5, 0
	s_add_u32 s42, s4, 0xf4b1100
	s_addc_u32 s43, s5, 0
	s_add_u32 s72, s4, 0xf4b1200
	s_addc_u32 s73, s5, 0
	s_add_u32 s74, s4, 0xf4b1300
	s_addc_u32 s75, s5, 0
	s_mov_b32 s44, 1
	s_branch .LBB0_475

.LBB0_564:
	s_or_b64 exec, exec, s[6:7]
	s_mov_b64 s[4:5], s[0:1]
	v_readlane_b32 s34, v255, 2
	s_waitcnt vmcnt(0)
	v_mov_b32_e32 v0, v252
	s_barrier
	s_nop 0
	v_cmp_eq_u32_e32 vcc, 0, v0
	s_and_saveexec_b64 s[2:3], vcc
	s_cbranch_execz .LBB0_616
	v_readlane_b32 s6, v255, 9
	v_readlane_b32 s4, v255, 0
	v_readlane_b32 s5, v255, 1
	s_waitcnt vmcnt(0) expcnt(0) lgkmcnt(0)
	v_mov_b32_e32 v0, s6
	ds_read_b32 v3, v0
	v_readlane_b32 s6, v255, 10
	s_waitcnt lgkmcnt(0)
	v_cmp_ne_u32_e32 vcc, 0, v3
	v_mov_b32_e32 v0, s6
	ds_read_b32 v2, v0
	s_cbranch_vccnz .LBB0_580
	s_add_u32 s6, s4, 0xf4b0200
	s_addc_u32 s7, s5, 0
	s_add_u32 s8, s4, 0xf4b0400
	s_addc_u32 s9, s5, 0
	s_add_u32 s10, s4, 0xf4b0500
	s_addc_u32 s11, s5, 0
	s_add_u32 s12, s4, 0xf4b0600
	s_addc_u32 s13, s5, 0
	s_add_u32 s14, s4, 0xf4b0700
	s_addc_u32 s15, s5, 0
	s_add_u32 s16, s4, 0xf4b0800
	s_addc_u32 s17, s5, 0
	s_add_u32 s86, s4, 0xf4b0900
	s_addc_u32 s87, s5, 0
	s_add_u32 s88, s4, 0xf4b0a00
	s_addc_u32 s89, s5, 0
	s_add_u32 s90, s4, 0xf4b0b00
	s_addc_u32 s91, s5, 0
	s_mov_b64 s[78:79], s[92:93]
	s_add_u32 s92, s4, 0xf4b0c00
	s_addc_u32 s93, s5, 0
	s_add_u32 s94, s4, 0xf4b0d00
	s_addc_u32 s95, s5, 0
	s_add_u32 s96, s4, 0xf4b0e00
	s_addc_u32 s97, s5, 0
	s_add_u32 s38, s4, 0xf4b0f00
	s_addc_u32 s39, s5, 0
	s_add_u32 s36, s4, 0xf4b1000
	s_addc_u32 s37, s5, 0
	s_add_u32 s42, s4, 0xf4b1100
	s_addc_u32 s43, s5, 0
	s_add_u32 s72, s4, 0xf4b1200
	s_addc_u32 s73, s5, 0
	s_add_u32 s74, s4, 0xf4b1300
	s_addc_u32 s75, s5, 0
	s_mov_b32 s44, 1
	s_branch .LBB0_568

.LBB0_858:
	s_mov_b64 s[4:5], s[0:1]
	v_readlane_b32 s34, v255, 2
	s_waitcnt vmcnt(0)
	v_mov_b32_e32 v0, v252
	s_waitcnt lgkmcnt(0)
	s_barrier
	s_nop 0
	v_cmp_eq_u32_e32 vcc, 0, v0
	s_and_saveexec_b64 s[2:3], vcc
	s_cbranch_execz .LBB0_911
	v_readlane_b32 s6, v255, 9
	v_readlane_b32 s4, v255, 0
	v_readlane_b32 s5, v255, 1
	s_waitcnt vmcnt(0) expcnt(0) lgkmcnt(0)
	v_mov_b32_e32 v0, s6
	ds_read_b32 v3, v0
	v_readlane_b32 s6, v255, 10
	s_waitcnt lgkmcnt(0)
	v_cmp_ne_u32_e32 vcc, 0, v3
	v_mov_b32_e32 v0, s6
	ds_read_b32 v2, v0
	s_cbranch_vccnz .LBB0_875
	s_add_u32 s6, s4, 0xf4b0200
	s_addc_u32 s7, s5, 0
	s_add_u32 s12, s4, 0xf4b0400
	s_addc_u32 s13, s5, 0
	s_add_u32 s14, s4, 0xf4b0500
	s_addc_u32 s15, s5, 0
	s_add_u32 s16, s4, 0xf4b0600
	s_addc_u32 s17, s5, 0
	s_add_u32 s84, s4, 0xf4b0700
	s_addc_u32 s85, s5, 0
	s_add_u32 s86, s4, 0xf4b0800
	s_addc_u32 s87, s5, 0
	s_add_u32 s88, s4, 0xf4b0900
	s_addc_u32 s89, s5, 0
	s_add_u32 s90, s4, 0xf4b0a00
	s_addc_u32 s91, s5, 0
	s_add_u32 s92, s4, 0xf4b0b00
	s_addc_u32 s93, s5, 0
	s_add_u32 s94, s4, 0xf4b0c00
	s_addc_u32 s95, s5, 0
	s_add_u32 s96, s4, 0xf4b0d00
	s_addc_u32 s97, s5, 0
	s_add_u32 s38, s4, 0xf4b0e00
	s_addc_u32 s39, s5, 0
	s_add_u32 s36, s4, 0xf4b0f00
	s_addc_u32 s37, s5, 0
	s_add_u32 s42, s4, 0xf4b1000
	s_addc_u32 s43, s5, 0
	s_add_u32 s72, s4, 0xf4b1100
	s_addc_u32 s73, s5, 0
	s_add_u32 s74, s4, 0xf4b1200
	s_addc_u32 s75, s5, 0
	s_add_u32 s28, s4, 0xf4b1300
	s_addc_u32 s29, s5, 0
	s_mov_b32 s44, 1
	s_branch .LBB0_862

.LBB0_877:
	s_or_b64 exec, exec, s[12:13]
	v_cvt_f32_u32_e32 v5, v3
	s_waitcnt vmcnt(0)
	v_readfirstlane_b32 s6, v4
	v_sub_u32_e32 v4, 0, v3
	v_rcp_iflag_f32_e32 v5, v5
	v_add_u32_e32 v6, s6, v0
	v_mul_f32_e32 v5, 0x4f7ffffe, v5
	v_cvt_u32_f32_e32 v5, v5
	v_mul_lo_u32 v0, v4, v5
	v_mul_hi_u32 v0, v5, v0
	v_add_u32_e32 v0, v5, v0
	v_mul_hi_u32 v0, v6, v0
	v_mul_lo_u32 v4, v0, v3
	v_sub_u32_e32 v4, v6, v4
	v_add_u32_e32 v5, 1, v0
	v_cmp_ge_u32_e32 vcc, v4, v3
	s_nop 1
	v_cndmask_b32_e32 v0, v0, v5, vcc
	v_sub_u32_e32 v5, v4, v3
	v_cndmask_b32_e32 v4, v4, v5, vcc
	v_add_u32_e32 v5, 1, v0
	v_cmp_ge_u32_e32 vcc, v4, v3
	v_add_u32_e32 v4, 1, v6
	s_nop 0
	v_cndmask_b32_e32 v0, v0, v5, vcc
	v_mul_lo_u32 v5, v3, v0
	v_add_u32_e32 v3, v5, v3
	v_cmp_ne_u32_e32 vcc, v4, v3
	s_and_saveexec_b64 s[6:7], vcc
	s_xor_b64 s[6:7], exec, s[6:7]
	s_cbranch_execz .LBB0_891
	s_add_i32 s34, s47, 0x900
	s_lshl_b64 s[12:13], s[34:35], 2
	s_add_u32 s16, s4, 0xf4b3500
	s_addc_u32 s17, s5, 0
	s_waitcnt lgkmcnt(0)
	global_load_dword v2, v1, s[16:17] sc1
	s_waitcnt vmcnt(0)
	v_cmp_eq_u32_e32 vcc, v2, v0
	s_and_saveexec_b64 s[12:13], vcc
	s_cbranch_execz .LBB0_890
	s_add_u32 s14, s4, 0xf4b0200
	s_addc_u32 s15, s5, 0
	s_mov_b32 s34, 1
	s_mov_b64 s[28:29], 0
	s_branch .LBB0_881

.LBB0_936:
	s_mov_b64 s[4:5], s[0:1]
	v_readlane_b32 s34, v255, 2
	s_waitcnt vmcnt(0)
	v_mov_b32_e32 v0, v252
	s_barrier
	s_nop 0
	v_cmp_eq_u32_e32 vcc, 0, v0
	s_and_saveexec_b64 s[2:3], vcc
	s_cbranch_execz .LBB0_988
	v_readlane_b32 s6, v255, 9
	v_readlane_b32 s4, v255, 0
	v_readlane_b32 s5, v255, 1
	s_waitcnt vmcnt(0) expcnt(0) lgkmcnt(0)
	v_mov_b32_e32 v0, s6
	ds_read_b32 v3, v0
	v_readlane_b32 s6, v255, 10
	s_waitcnt lgkmcnt(0)
	v_cmp_ne_u32_e32 vcc, 0, v3
	v_mov_b32_e32 v0, s6
	ds_read_b32 v2, v0
	s_cbranch_vccnz .LBB0_952
	s_add_u32 s6, s4, 0xf4b0200
	s_addc_u32 s7, s5, 0
	s_add_u32 s12, s4, 0xf4b0400
	s_addc_u32 s13, s5, 0
	s_add_u32 s14, s4, 0xf4b0500
	s_addc_u32 s15, s5, 0
	s_add_u32 s16, s4, 0xf4b0600
	s_addc_u32 s17, s5, 0
	s_add_u32 s84, s4, 0xf4b0700
	s_addc_u32 s85, s5, 0
	s_add_u32 s86, s4, 0xf4b0800
	s_addc_u32 s87, s5, 0
	s_add_u32 s88, s4, 0xf4b0900
	s_addc_u32 s89, s5, 0
	s_add_u32 s90, s4, 0xf4b0a00
	s_addc_u32 s91, s5, 0
	s_add_u32 s92, s4, 0xf4b0b00
	s_addc_u32 s93, s5, 0
	s_add_u32 s94, s4, 0xf4b0c00
	s_addc_u32 s95, s5, 0
	s_add_u32 s96, s4, 0xf4b0d00
	s_addc_u32 s97, s5, 0
	s_add_u32 s38, s4, 0xf4b0e00
	s_addc_u32 s39, s5, 0
	s_add_u32 s36, s4, 0xf4b0f00
	s_addc_u32 s37, s5, 0
	s_add_u32 s42, s4, 0xf4b1000
	s_addc_u32 s43, s5, 0
	s_add_u32 s72, s4, 0xf4b1100
	s_addc_u32 s73, s5, 0
	s_add_u32 s74, s4, 0xf4b1200
	s_mov_b32 s45, s75
	s_addc_u32 s75, s5, 0
	s_add_u32 s28, s4, 0xf4b1300
	s_addc_u32 s29, s5, 0
	s_mov_b32 s44, 1
	s_branch .LBB0_940

.LBB0_1005:
	s_or_b64 exec, exec, s[4:5]
	s_mov_b64 s[4:5], s[0:1]
	v_readlane_b32 s34, v255, 2
	s_waitcnt vmcnt(0)
	v_mov_b32_e32 v0, v252
	s_barrier
	s_nop 0
	v_cmp_eq_u32_e32 vcc, 0, v0
	s_and_saveexec_b64 s[2:3], vcc
	s_cbranch_execz .LBB0_1057
	v_readlane_b32 s6, v255, 9
	v_readlane_b32 s4, v255, 0
	v_readlane_b32 s5, v255, 1
	s_waitcnt vmcnt(0) expcnt(0) lgkmcnt(0)
	v_mov_b32_e32 v0, s6
	ds_read_b32 v3, v0
	v_readlane_b32 s6, v255, 10
	s_waitcnt lgkmcnt(0)
	v_cmp_ne_u32_e32 vcc, 0, v3
	v_mov_b32_e32 v0, s6
	ds_read_b32 v2, v0
	s_cbranch_vccnz .LBB0_1021
	s_add_u32 s6, s4, 0xf4b0200
	s_addc_u32 s7, s5, 0
	s_add_u32 s12, s4, 0xf4b0400
	s_addc_u32 s13, s5, 0
	s_add_u32 s14, s4, 0xf4b0500
	s_addc_u32 s15, s5, 0
	s_add_u32 s16, s4, 0xf4b0600
	s_addc_u32 s17, s5, 0
	s_add_u32 s84, s4, 0xf4b0700
	s_addc_u32 s85, s5, 0
	s_add_u32 s86, s4, 0xf4b0800
	s_addc_u32 s87, s5, 0
	s_add_u32 s88, s4, 0xf4b0900
	s_addc_u32 s89, s5, 0
	s_add_u32 s90, s4, 0xf4b0a00
	s_addc_u32 s91, s5, 0
	s_add_u32 s92, s4, 0xf4b0b00
	s_addc_u32 s93, s5, 0
	s_add_u32 s94, s4, 0xf4b0c00
	s_addc_u32 s95, s5, 0
	s_add_u32 s96, s4, 0xf4b0d00
	s_addc_u32 s97, s5, 0
	s_add_u32 s38, s4, 0xf4b0e00
	s_addc_u32 s39, s5, 0
	s_add_u32 s36, s4, 0xf4b0f00
	s_addc_u32 s37, s5, 0
	s_add_u32 s42, s4, 0xf4b1000
	s_addc_u32 s43, s5, 0
	s_add_u32 s72, s4, 0xf4b1100
	s_addc_u32 s73, s5, 0
	s_add_u32 s74, s4, 0xf4b1200
	s_addc_u32 s75, s5, 0
	s_add_u32 s28, s4, 0xf4b1300
	s_addc_u32 s29, s5, 0
	s_mov_b32 s44, 1
	s_branch .LBB0_1009

.LBB0_1232:
	v_readlane_b32 s6, v255, 9
	v_readlane_b32 s4, v255, 0
	v_readlane_b32 s5, v255, 1
	s_waitcnt vmcnt(0) expcnt(0) lgkmcnt(0)
	v_mov_b32_e32 v0, s6
	ds_read_b32 v3, v0
	v_readlane_b32 s6, v255, 10
	s_waitcnt lgkmcnt(0)
	v_cmp_ne_u32_e32 vcc, 0, v3
	v_mov_b32_e32 v0, s6
	ds_read_b32 v2, v0
	s_cbranch_vccnz .LBB0_1247
	s_add_u32 s6, s4, 0xf4b0200
	s_addc_u32 s7, s5, 0
	s_add_u32 s8, s4, 0xf4b0400
	s_addc_u32 s9, s5, 0
	s_add_u32 s10, s4, 0xf4b0500
	s_addc_u32 s11, s5, 0
	s_add_u32 s12, s4, 0xf4b0600
	s_addc_u32 s13, s5, 0
	s_add_u32 s14, s4, 0xf4b0700
	s_addc_u32 s15, s5, 0
	s_add_u32 s16, s4, 0xf4b0800
	s_addc_u32 s17, s5, 0
	s_add_u32 s80, s4, 0xf4b0900
	s_addc_u32 s81, s5, 0
	s_add_u32 s82, s4, 0xf4b0a00
	s_addc_u32 s83, s5, 0
	s_add_u32 s84, s4, 0xf4b0b00
	s_addc_u32 s85, s5, 0
	s_add_u32 s86, s4, 0xf4b0c00
	s_addc_u32 s87, s5, 0
	s_add_u32 s88, s4, 0xf4b0d00
	s_addc_u32 s89, s5, 0
	s_add_u32 s38, s4, 0xf4b0e00
	s_addc_u32 s39, s5, 0
	s_add_u32 s36, s4, 0xf4b0f00
	s_addc_u32 s37, s5, 0
	s_add_u32 s42, s4, 0xf4b1000
	s_addc_u32 s43, s5, 0
	s_add_u32 s72, s4, 0xf4b1100
	s_addc_u32 s73, s5, 0
	s_add_u32 s74, s4, 0xf4b1200
	s_addc_u32 s75, s5, 0
	s_add_u32 s28, s4, 0xf4b1300
	s_addc_u32 s29, s5, 0
	s_mov_b32 s44, 1
	s_branch .LBB0_1235
